# add P2b rope loads issued together (cos/sin load no longer behind the first k_rope wait)
# speedup vs baseline: 1.0068x; 1.0039x over previous
; __device__ __forceinline__ float bf2f(unsigned short u) { return __uint_as_float((unsigned)u << 16); }
; __device__ __forceinline__ unsigned short f2bf(float f) { unsigned u = __float_as_uint(f); return (unsigned short)((u + 0x7fffu + ((u >> 16) & 1u)) >> 16); }
; __device__ __forceinline__ unsigned pk2(float lo, float hi) { return pg8::cvtpk(lo, hi); }
; __device__ __forceinline__ void p2b_rows(const Params& P, int G) {
;     ...
;         const u32x4 a = *(const u32x4*)(zr + ZO_CQ + 8 * lane); const u32x2 k = *(const u32x2*)(zr + ZO_CKV + 4 * lane);
;         float s1 = 0.f, s2 = 0.f;
; #pragma unroll
;         for (int e = 0; e < 4; ++e) { const float lo = __uint_as_float(a[e] << 16), hi = __uint_as_float(a[e] & 0xffff0000u); s1 += lo * lo + hi * hi; }
; #pragma unroll
;         for (int e = 0; e < 2; ++e) { const float lo = __uint_as_float(k[e] << 16), hi = __uint_as_float(k[e] & 0xffff0000u); s2 += lo * lo + hi * hi; }
;         s1 = wave_sum(s1); s2 = wave_sum(s2);
;         const float r1 = rsqrtf(s1 * (1.0f / 512.0f) + RMS_EPS), r2 = rsqrtf(s2 * (1.0f / 256.0f) + RMS_EPS);
;         { u32x4 w;
; #pragma unroll
;           for (int e = 0; e < 4; ++e) w[e] = pk2(__uint_as_float(a[e] << 16) * r1, __uint_as_float(a[e] & 0xffff0000u) * r1);
;           *(u32x4*)(CQN + (size_t)m * 512 + 8 * lane) = w;
;           u32x2 w2;
; #pragma unroll
;           for (int e = 0; e < 2; ++e) w2[e] = pk2(__uint_as_float(k[e] << 16) * r2, __uint_as_float(k[e] & 0xffff0000u) * r2);
;           *(u32x2*)(CKVN + (size_t)m * 256 + 4 * lane) = w2; }
;         if (lane < 32) { const float x1 = bf2f(zr[ZO_KR + lane]), x2 = bf2f(zr[ZO_KR + 32 + lane]); const float c = cs[(size_t)m * 64 + 2 * lane], s = cs[(size_t)m * 64 + 2 * lane + 1];
;             KR[(size_t)m * 64 + lane] = f2bf(x1 * c - x2 * s); KR[(size_t)m * 64 + 32 + lane] = f2bf(x2 * c + x1 * s); }
.LBB0_300:
	v_lshl_add_u64 v[26:27], v[16:17], 0, v[12:13]
	global_load_dwordx4 v[26:29], v[26:27], off
	v_lshl_add_u64 v[30:31], v[16:17], 0, v[2:3]
	global_load_dwordx2 v[30:31], v[30:31], off offset:1024
	s_waitcnt vmcnt(1)
	v_and_b32_e32 v33, 0xffff0000, v29
	v_and_b32_e32 v35, 0xffff0000, v28
	v_lshlrev_b32_e32 v32, 16, v29
	v_lshlrev_b32_e32 v34, 16, v28
	v_mov_b32_e32 v36, v33
	v_mov_b32_e32 v37, v35
	v_mov_b32_e32 v28, v32
	v_mov_b32_e32 v29, v34
	v_pk_mul_f32 v[36:37], v[36:37], v[36:37]
	v_and_b32_e32 v39, 0xffff0000, v26
	v_pk_fma_f32 v[28:29], v[28:29], v[28:29], v[36:37]
	v_and_b32_e32 v37, 0xffff0000, v27
	v_lshlrev_b32_e32 v36, 16, v27
	v_lshlrev_b32_e32 v38, 16, v26
	v_mov_b32_e32 v26, v39
	v_mov_b32_e32 v27, v37
	v_pk_mul_f32 v[26:27], v[26:27], v[26:27]
	v_mov_b32_e32 v40, v38
	v_mov_b32_e32 v41, v36
	s_waitcnt vmcnt(0)
	v_and_b32_e32 v43, 0xffff0000, v31
	v_and_b32_e32 v45, 0xffff0000, v30
	v_pk_fma_f32 v[26:27], v[40:41], v[40:41], v[26:27]
	v_lshlrev_b32_e32 v42, 16, v31
	v_lshlrev_b32_e32 v44, 16, v30
	v_mov_b32_e32 v46, v45
	v_mov_b32_e32 v47, v43
	v_add_f32_e32 v26, v26, v27
	v_mov_b32_e32 v30, v44
	v_mov_b32_e32 v31, v42
	v_pk_mul_f32 v[46:47], v[46:47], v[46:47]
	v_pk_add_f32 v[26:27], v[28:29], v[26:27] op_sel_hi:[1,0]
	v_pk_fma_f32 v[30:31], v[30:31], v[30:31], v[46:47]
	v_mov_b32_e32 v47, v28
	v_mov_b32_e32 v46, v30
	v_mov_b32_e32 v26, v31
	v_pk_add_f32 v[26:27], v[46:47], v[26:27]
	ds_bpermute_b32 v29, v19, v27
	ds_bpermute_b32 v28, v19, v26
	v_lshl_add_u64 v[40:41], s[58:59], 0, v[14:15]
	s_waitcnt lgkmcnt(0)
	v_pk_add_f32 v[26:27], v[26:27], v[28:29]
	ds_bpermute_b32 v29, v20, v27
	ds_bpermute_b32 v28, v20, v26
	s_waitcnt lgkmcnt(0)
	v_pk_add_f32 v[26:27], v[26:27], v[28:29]
	ds_bpermute_b32 v29, v21, v27
	ds_bpermute_b32 v28, v21, v26
	s_waitcnt lgkmcnt(0)
	v_pk_add_f32 v[26:27], v[26:27], v[28:29]
	ds_bpermute_b32 v29, v22, v27
	ds_bpermute_b32 v28, v22, v26
	s_waitcnt lgkmcnt(0)
	v_pk_add_f32 v[26:27], v[26:27], v[28:29]
	ds_bpermute_b32 v29, v23, v27
	ds_bpermute_b32 v28, v23, v26
	s_waitcnt lgkmcnt(0)
	v_pk_add_f32 v[26:27], v[26:27], v[28:29]
	ds_bpermute_b32 v29, v24, v27
	ds_bpermute_b32 v28, v24, v26
	s_waitcnt lgkmcnt(0)
	v_pk_add_f32 v[26:27], v[26:27], v[28:29]
	s_nop 0
	v_pk_fma_f32 v[30:31], v[26:27], s[52:53], v[18:19] op_sel_hi:[1,1,0]
	s_nop 0
	v_mul_f32_e32 v1, 0x4b800000, v31
	v_cmp_gt_f32_e64 s[38:39], s3, v31
	v_cmp_gt_f32_e32 vcc, s3, v30
	s_nop 0
	v_cndmask_b32_e64 v1, v31, v1, s[38:39]
	v_rsq_f32_e32 v1, v1
	s_nop 0
	v_mul_f32_e32 v25, 0x45800000, v1
	v_cndmask_b32_e64 v46, v1, v25, s[38:39]
	v_mul_f32_e32 v1, 0x4b800000, v30
	v_cndmask_b32_e32 v1, v30, v1, vcc
	v_rsq_f32_e32 v1, v1
	v_pk_mul_f32 v[26:27], v[46:47], v[38:39] op_sel_hi:[0,1]
	v_pk_mul_f32 v[28:29], v[46:47], v[36:37] op_sel_hi:[0,1]
	v_cvt_pk_bf16_f32 v26, v26, v27
	v_cvt_pk_bf16_f32 v27, v28, v29
	v_pk_mul_f32 v[28:29], v[46:47], v[34:35] op_sel_hi:[0,1]
	v_pk_mul_f32 v[32:33], v[46:47], v[32:33] op_sel_hi:[0,1]
	v_cvt_pk_bf16_f32 v28, v28, v29
	v_cvt_pk_bf16_f32 v29, v32, v33
	v_mul_f32_e32 v25, 0x45800000, v1
	global_store_dwordx4 v[40:41], v[26:29], off
	s_nop 1
	v_cndmask_b32_e32 v26, v1, v25, vcc
	v_pk_mul_f32 v[28:29], v[26:27], v[44:45] op_sel_hi:[0,1]
	v_pk_mul_f32 v[26:27], v[26:27], v[42:43] op_sel_hi:[0,1]
	v_cvt_pk_bf16_f32 v28, v28, v29
	v_cvt_pk_bf16_f32 v29, v26, v27
	v_lshl_add_u64 v[26:27], s[58:59], 0, v[10:11]
	global_store_dwordx2 v[26:27], v[28:29], off
	s_and_saveexec_b64 s[38:39], s[0:1]
	s_cbranch_execz .LBB0_299
	v_lshl_add_u64 v[26:27], v[16:17], 0, v[4:5]
	v_add_co_u32_e32 v26, vcc, 0x1000, v26
	v_lshl_add_u64 v[28:29], s[58:59], 0, v[8:9]
	s_nop 0
	v_addc_co_u32_e32 v27, vcc, 0, v27, vcc
	global_load_ushort v1, v[26:27], off offset:3584
	global_load_ushort v25, v[26:27], off offset:3648
	v_lshl_add_u64 v[26:27], s[58:59], 0, v[6:7]
	v_add_co_u32_e32 v26, vcc, 0x300000, v26
	s_nop 1
	v_addc_co_u32_e32 v27, vcc, 0, v27, vcc
	global_load_dwordx2 v[26:27], v[26:27], off
	s_waitcnt vmcnt(2)
	v_lshlrev_b32_e32 v1, 16, v1
	s_waitcnt vmcnt(1)
	v_lshlrev_b32_e32 v25, 16, v25
	v_add_co_u32_e32 v28, vcc, 0x700000, v28
	s_waitcnt vmcnt(0)
	v_mul_f32_e32 v30, v27, v25
	v_mul_f32_e32 v25, v26, v25
	v_fma_f32 v26, v26, v1, -v30
	v_fmac_f32_e32 v25, v27, v1
	v_bfe_u32 v1, v26, 16, 1
	v_addc_co_u32_e32 v29, vcc, 0, v29, vcc
	v_bfe_u32 v27, v25, 16, 1
	v_add3_u32 v1, v26, v1, s33
	v_add3_u32 v25, v25, v27, s33
	global_store_short_d16_hi v[28:29], v1, off
	global_store_short_d16_hi v[28:29], v25, off offset:64
	s_branch .LBB0_299
